# attention workgroups prefetch S5 GEMM operands (U2, B1, B3) into the memory-side cache at phase entry (fire-and-forget dword loads); plus on-chip Z carry scan
# speedup vs baseline: 1.0111x; 1.0020x over previous
; __global__ void __launch_bounds__(NTHR) hybrid_encoder_fwd(Params P) {
;     ...
;                     Gemm g3; g3.A = U2; g3.Bt = (const bf16_t*)(ws + WS_B3 + j * SZ_B3); g3.lda = 768; g3.ldb = 768; g3.K = 768;
;                     ListOrder S3; S3.total = 128; S3.G = 64; S3.c = bid; S3.mode = 2;
;                     EpiP3 E3; E3.Y = Y;
;                     gemm_phase<EpiP3, ListOrder>(lds, g3, S3, E3);
;                 } else {
;                     attn_a_phase(lds, bid - 64, 192, 8, Qb, Kb, Vb, P.in[1], NUM, ML);
.LBB0_479:
	s_mov_b64 s[20:21], 0x6404000
	s_and_b64 vcc, exec, s[0:1]
	s_cbranch_vccz .LBB0_726
	v_readlane_b32 s12, v254, 9
	v_mov_b32_e32 v142, v200
	v_readlane_b32 s13, v254, 10
	s_mov_b64 s[0:1], -1
	v_readfirstlane_b32 s34, v142
	s_and_b64 vcc, exec, s[12:13]
	s_cbranch_vccz .LBB0_573
	v_readlane_b32 s0, v252, 29
	s_sub_i32 s1, s2, 64
	s_lshl_b32 s44, s1, 9
	v_add_u32_e32 v1, s44, v200
	v_lshlrev_b32_e32 v1, 7, v1
	s_add_u32 s42, s96, 0x2b404000
	s_addc_u32 s43, s97, 0
	global_load_dword v251, v1, s[42:43]
	v_add_u32_e32 v133, 0xc00000, v1
	global_load_dword v251, v133, s[42:43]
	s_lshl_b32 s44, s0, 24
	s_add_u32 s44, s44, 0x1d404000
	s_add_u32 s42, s96, s44
	s_addc_u32 s43, s97, 0
	s_mul_i32 s44, s0, 0x3000000
	s_add_u32 s44, s44, 0x17404000
	s_add_u32 s44, s96, s44
	s_addc_u32 s45, s97, 0
	global_load_dword v251, v1, s[42:43]
	s_cmp_lt_u32 s1, 64
	s_cbranch_scc0 .Lpf_skip
	v_add_u32_e32 v133, 0xc00000, v1
	global_load_dword v251, v133, s[42:43]
.Lpf_skip:
	global_load_dword v251, v1, s[44:45]
	v_add_u32_e32 v133, 0xc00000, v1
	global_load_dword v251, v133, s[44:45]
	v_add_u32_e32 v133, 0x1800000, v1
	global_load_dword v251, v133, s[44:45]
	v_add_u32_e32 v133, 0x2400000, v1
	global_load_dword v251, v133, s[44:45]
	v_mov_b32_e32 v133, v200
	s_movk_i32 s0, 0xff
	s_nop 0
	v_cmp_lt_i32_e32 vcc, s0, v133
	s_and_saveexec_b64 s[0:1], vcc
	s_xor_b64 s[0:1], exec, s[0:1]
	v_lshrrev_b32_e32 v135, 4, v133
	s_or_saveexec_b64 s[0:1], s[0:1]
	v_lshlrev_b32_e32 v1, 4, v133
	s_waitcnt vmcnt(4)
	v_and_b32_e32 v69, 0xf0, v1
	s_xor_b64 exec, exec, s[0:1]
	s_cbranch_execz .LBB0_485
	v_ashrrev_i32_e32 v135, 4, v133
	v_add_u32_e32 v1, 0x100, v135
	s_mov_b32 s68, s69
	v_mul_lo_u32 v2, v1, s22
	s_mov_b32 s70, s69
	s_mov_b32 s71, s69
	v_mov_b64_e32 v[4:5], s[68:69]
	v_mul_lo_u32 v1, v1, s33
	v_readlane_b32 s12, v252, 22
	v_add3_u32 v2, 0, v2, v69
	v_mov_b64_e32 v[6:7], s[70:71]
	v_readlane_b32 s70, v252, 29
	v_add3_u32 v1, s12, v1, v69
	v_readlane_b32 s71, v252, 30
	ds_write_b128 v2, v[4:7]
	ds_write_b128 v1, v[4:7]
